# grid barrier: the L1 invalidate (acquire) is issued at barrier entry and completes under the wait; the post-release invalidate+wait is gone
# speedup vs baseline: 1.0167x; 1.0095x over previous
.LBB0_45:
	s_waitcnt vmcnt(0)
	s_waitcnt lgkmcnt(0)
	s_setprio 0
	s_barrier
	s_mov_b64 s[6:7], exec
	v_readlane_b32 s0, v255, 4
	v_readlane_b32 s1, v255, 5
	s_and_b64 s[0:1], s[6:7], s[0:1]
	v_writelane_b32 v255, s29, 9
	s_mov_b64 exec, s[0:1]
	s_cbranch_execz .LBB0_97
	s_add_i32 s0, 0, 0x25800
	v_mov_b32_e32 v0, s0
	s_waitcnt vmcnt(0) expcnt(0) lgkmcnt(0)
	buffer_inv sc1
	ds_read_b32 v2, v0
	s_add_i32 s0, 0, 0x25804
	v_mov_b32_e32 v0, s0
	ds_read_b32 v0, v0
	s_waitcnt lgkmcnt(1)
	v_cmp_ne_u32_e32 vcc, 0, v2
	s_cbranch_vccnz .LBB0_61
	s_add_u32 s8, s26, 0xc0200
	s_addc_u32 s9, s27, 0
	s_add_u32 s4, s26, 0xc0400
	s_addc_u32 s5, s27, 0
	s_add_u32 s10, s26, 0xc0500
	s_addc_u32 s11, s27, 0
	s_add_u32 s12, s26, 0xc0600
	s_addc_u32 s13, s27, 0
	s_add_u32 s14, s26, 0xc0700
	s_addc_u32 s15, s27, 0
	s_add_u32 s16, s26, 0xc0800
	s_addc_u32 s17, s27, 0
	s_add_u32 s18, s26, 0xc0900
	s_addc_u32 s19, s27, 0
	s_add_u32 s20, s26, 0xc0a00
	s_addc_u32 s21, s27, 0
	s_add_u32 s36, s26, 0xc0b00
	s_addc_u32 s37, s27, 0
	s_add_u32 s38, s26, 0xc0c00
	s_addc_u32 s39, s27, 0
	s_add_u32 s40, s26, 0xc0d00
	s_addc_u32 s41, s27, 0
	s_add_u32 s42, s26, 0xc0e00
	s_addc_u32 s43, s27, 0
	s_add_u32 s44, s26, 0xc0f00
	s_addc_u32 s45, s27, 0
	s_add_u32 s46, s26, 0xc1000
	s_load_dword s0, s[88:89], 0x180
	s_addc_u32 s47, s27, 0
	s_add_u32 s48, s26, 0xc1100
	s_addc_u32 s49, s27, 0
	s_add_u32 s50, s26, 0xc1200
	s_addc_u32 s51, s27, 0
	s_waitcnt lgkmcnt(0)
	s_mul_i32 s23, s31, s0
	s_add_u32 s52, s26, 0xc1300
	s_mul_i32 s23, s23, s30
	s_addc_u32 s53, s27, 0
	s_mov_b32 s24, 1
	v_mov_b32_e32 v16, 0
	s_branch .LBB0_49

.LBB0_76:
	s_or_b64 exec, exec, s[0:1]
	s_waitcnt vmcnt(0)
.LBB0_77:
	s_andn2_saveexec_b64 s[0:1], s[4:5]
	s_cbranch_execz .LBB0_97
	s_mov_b64 s[0:1], exec
	buffer_wbl2 sc1
	s_waitcnt lgkmcnt(0)
	s_waitcnt vmcnt(0)
	v_mbcnt_lo_u32_b32 v1, s0, 0
	v_mbcnt_hi_u32_b32 v1, s1, v1
	v_cmp_eq_u32_e32 vcc, 0, v1
	s_and_saveexec_b64 s[4:5], vcc
	s_cbranch_execz .LBB0_80
	s_bcnt1_i32_b64 s0, s[0:1]
	v_mov_b32_e32 v2, 0xc3000
	v_mov_b32_e32 v3, s0
	global_atomic_add v2, v2, v3, s[26:27] offset:1024 sc0

.LBB0_243:
	s_waitcnt vmcnt(0)
	s_setprio 0
	s_barrier
	s_mov_b64 s[0:1], exec
	v_readlane_b32 s4, v255, 4
	v_readlane_b32 s5, v255, 5
	s_and_b64 s[4:5], s[0:1], s[4:5]
	s_xor_b64 s[6:7], s[4:5], s[0:1]
	s_mov_b64 exec, s[4:5]
	s_cbranch_execz .LBB0_296
	s_add_i32 s0, 0, 0x25800
	v_mov_b32_e32 v0, s0
	s_waitcnt vmcnt(0) expcnt(0) lgkmcnt(0)
	buffer_inv sc1
	ds_read_b32 v2, v0
	s_add_i32 s0, 0, 0x25804
	v_mov_b32_e32 v0, s0
	ds_read_b32 v0, v0
	s_waitcnt lgkmcnt(1)
	v_cmp_ne_u32_e32 vcc, 0, v2
	s_cbranch_vccnz .LBB0_259
	s_add_u32 s8, s26, 0xc0200
	s_addc_u32 s9, s27, 0
	s_add_u32 s4, s26, 0xc0400
	s_addc_u32 s5, s27, 0
	s_add_u32 s10, s26, 0xc0500
	s_addc_u32 s11, s27, 0
	s_add_u32 s12, s26, 0xc0600
	s_addc_u32 s13, s27, 0
	s_add_u32 s14, s26, 0xc0700
	s_addc_u32 s15, s27, 0
	s_add_u32 s16, s26, 0xc0800
	s_addc_u32 s17, s27, 0
	s_add_u32 s36, s26, 0xc0900
	s_addc_u32 s37, s27, 0
	s_add_u32 s40, s26, 0xc0a00
	s_addc_u32 s41, s27, 0
	s_add_u32 s42, s26, 0xc0b00
	s_addc_u32 s43, s27, 0
	s_add_u32 s44, s26, 0xc0c00
	s_addc_u32 s45, s27, 0
	s_add_u32 s46, s26, 0xc0d00
	s_addc_u32 s47, s27, 0
	s_add_u32 s48, s26, 0xc0e00
	s_addc_u32 s49, s27, 0
	s_add_u32 s50, s26, 0xc0f00
	s_addc_u32 s51, s27, 0
	s_add_u32 s52, s26, 0xc1000
	s_load_dword s0, s[88:89], 0x180
	s_addc_u32 s53, s27, 0
	s_add_u32 s54, s26, 0xc1100
	s_addc_u32 s55, s27, 0
	s_add_u32 s56, s26, 0xc1200
	s_addc_u32 s57, s27, 0
	s_waitcnt lgkmcnt(0)
	s_mul_i32 s23, s31, s0
	s_add_u32 s58, s26, 0xc1300
	s_mul_i32 s23, s23, s30
	s_addc_u32 s59, s27, 0
	s_mov_b32 s24, 1
	v_mov_b32_e32 v16, 0
	s_branch .LBB0_247

.LBB0_274:
	s_or_b64 exec, exec, s[0:1]
	s_waitcnt vmcnt(0)
.LBB0_275:
	s_andn2_saveexec_b64 s[10:11], s[4:5]
	s_cbranch_execz .LBB0_295
	s_mov_b64 s[0:1], exec
	buffer_wbl2 sc1
	s_waitcnt lgkmcnt(0)
	s_waitcnt vmcnt(0)
	v_mbcnt_lo_u32_b32 v1, s0, 0
	v_mbcnt_hi_u32_b32 v1, s1, v1
	v_cmp_eq_u32_e32 vcc, 0, v1
	s_and_saveexec_b64 s[4:5], vcc
	s_cbranch_execz .LBB0_278
	s_bcnt1_i32_b64 s0, s[0:1]
	v_mov_b32_e32 v2, 0xc3000
	v_mov_b32_e32 v3, s0
	global_atomic_add v2, v2, v3, s[26:27] offset:1024 sc0

.LBB0_474:
	s_waitcnt vmcnt(0)
	s_waitcnt vmcnt(0) lgkmcnt(0)
	s_setprio 0
	s_barrier
	s_mov_b64 s[0:1], exec
	v_readlane_b32 s4, v255, 4
	v_readlane_b32 s5, v255, 5
	s_and_b64 s[4:5], s[0:1], s[4:5]
	s_xor_b64 s[6:7], s[4:5], s[0:1]
	s_mov_b64 exec, s[4:5]
	s_cbranch_execz .LBB0_527
	s_add_i32 s0, 0, 0x25800
	v_mov_b32_e32 v0, s0
	s_waitcnt vmcnt(0) expcnt(0) lgkmcnt(0)
	buffer_inv sc1
	ds_read_b32 v2, v0
	s_add_i32 s0, 0, 0x25804
	v_mov_b32_e32 v0, s0
	ds_read_b32 v0, v0
	s_waitcnt lgkmcnt(1)
	v_cmp_ne_u32_e32 vcc, 0, v2
	s_cbranch_vccnz .LBB0_490
	s_add_u32 s8, s26, 0xc0200
	s_addc_u32 s9, s27, 0
	s_add_u32 s4, s26, 0xc0400
	s_addc_u32 s5, s27, 0
	s_add_u32 s10, s26, 0xc0500
	s_addc_u32 s11, s27, 0
	s_add_u32 s12, s26, 0xc0600
	s_addc_u32 s13, s27, 0
	s_add_u32 s14, s26, 0xc0700
	s_addc_u32 s15, s27, 0
	s_add_u32 s36, s26, 0xc0800
	s_addc_u32 s37, s27, 0
	s_add_u32 s40, s26, 0xc0900
	s_addc_u32 s41, s27, 0
	s_add_u32 s42, s26, 0xc0a00
	s_addc_u32 s43, s27, 0
	s_add_u32 s44, s26, 0xc0b00
	s_addc_u32 s45, s27, 0
	s_add_u32 s50, s26, 0xc0c00
	s_addc_u32 s51, s27, 0
	s_add_u32 s52, s26, 0xc0d00
	s_addc_u32 s53, s27, 0
	s_add_u32 s54, s26, 0xc0e00
	s_addc_u32 s55, s27, 0
	s_add_u32 s56, s26, 0xc0f00
	s_addc_u32 s57, s27, 0
	s_add_u32 s58, s26, 0xc1000
	s_addc_u32 s59, s27, 0
	s_add_u32 s60, s26, 0xc1100
	s_addc_u32 s61, s27, 0
	s_add_u32 s62, s26, 0xc1200
	v_readlane_b32 s0, v255, 0
	s_addc_u32 s63, s27, 0
	s_mul_i32 s20, s31, s0
	s_add_u32 s64, s26, 0xc1300
	s_mul_i32 s20, s20, s30
	s_addc_u32 s65, s27, 0
	s_mov_b32 s21, 1
	v_mov_b32_e32 v16, 0
	s_branch .LBB0_478

.LBB0_505:
	s_or_b64 exec, exec, s[0:1]
	s_waitcnt vmcnt(0)
.LBB0_506:
	s_andn2_saveexec_b64 s[10:11], s[4:5]
	s_cbranch_execz .LBB0_526
	s_mov_b64 s[0:1], exec
	buffer_wbl2 sc1
	s_waitcnt lgkmcnt(0)
	s_waitcnt vmcnt(0)
	v_mbcnt_lo_u32_b32 v1, s0, 0
	v_mbcnt_hi_u32_b32 v1, s1, v1
	v_cmp_eq_u32_e32 vcc, 0, v1
	s_and_saveexec_b64 s[4:5], vcc
	s_cbranch_execz .LBB0_509
	s_bcnt1_i32_b64 s0, s[0:1]
	v_mov_b32_e32 v2, 0xc3000
	v_mov_b32_e32 v3, s0
	global_atomic_add v2, v2, v3, s[26:27] offset:1024 sc0

.LBB0_547:
	s_waitcnt vmcnt(0)
	s_waitcnt vmcnt(0) lgkmcnt(0)
	s_setprio 0
	s_barrier
	s_mov_b64 s[0:1], exec
	v_readlane_b32 s4, v255, 4
	v_readlane_b32 s5, v255, 5
	s_and_b64 s[4:5], s[0:1], s[4:5]
	s_xor_b64 s[6:7], s[4:5], s[0:1]
	s_mov_b64 exec, s[4:5]
	s_cbranch_execz .LBB0_600
	s_add_i32 s0, 0, 0x25800
	v_mov_b32_e32 v0, s0
	s_waitcnt vmcnt(0) expcnt(0) lgkmcnt(0)
	buffer_inv sc1
	ds_read_b32 v2, v0
	s_add_i32 s0, 0, 0x25804
	v_mov_b32_e32 v0, s0
	ds_read_b32 v0, v0
	s_waitcnt lgkmcnt(1)
	v_cmp_ne_u32_e32 vcc, 0, v2
	s_cbranch_vccnz .LBB0_563
	s_add_u32 s8, s26, 0xc0200
	s_addc_u32 s9, s27, 0
	s_add_u32 s4, s26, 0xc0400
	s_addc_u32 s5, s27, 0
	s_add_u32 s10, s26, 0xc0500
	s_addc_u32 s11, s27, 0
	s_add_u32 s12, s26, 0xc0600
	s_addc_u32 s13, s27, 0
	s_add_u32 s14, s26, 0xc0700
	s_addc_u32 s15, s27, 0
	s_add_u32 s16, s26, 0xc0800
	s_addc_u32 s17, s27, 0
	s_add_u32 s18, s26, 0xc0900
	s_addc_u32 s19, s27, 0
	s_add_u32 s36, s26, 0xc0a00
	s_addc_u32 s37, s27, 0
	s_add_u32 s40, s26, 0xc0b00
	s_addc_u32 s41, s27, 0
	s_add_u32 s42, s26, 0xc0c00
	s_addc_u32 s43, s27, 0
	s_add_u32 s44, s26, 0xc0d00
	s_addc_u32 s45, s27, 0
	s_add_u32 s50, s26, 0xc0e00
	s_addc_u32 s51, s27, 0
	s_add_u32 s54, s26, 0xc0f00
	s_addc_u32 s55, s27, 0
	s_add_u32 s58, s26, 0xc1000
	s_addc_u32 s59, s27, 0
	s_add_u32 s62, s26, 0xc1100
	s_addc_u32 s63, s27, 0
	s_add_u32 s64, s26, 0xc1200
	v_readlane_b32 s0, v255, 0
	s_addc_u32 s65, s27, 0
	s_mul_i32 s20, s31, s0
	s_add_u32 s66, s26, 0xc1300
	s_mul_i32 s20, s20, s30
	s_addc_u32 s67, s27, 0
	s_mov_b32 s21, 1
	v_mov_b32_e32 v16, 0
	s_branch .LBB0_551

.LBB0_578:
	s_or_b64 exec, exec, s[0:1]
	s_waitcnt vmcnt(0)
.LBB0_579:
	s_andn2_saveexec_b64 s[10:11], s[4:5]
	s_cbranch_execz .LBB0_599
	s_mov_b64 s[0:1], exec
	buffer_wbl2 sc1
	s_waitcnt lgkmcnt(0)
	s_waitcnt vmcnt(0)
	v_mbcnt_lo_u32_b32 v1, s0, 0
	v_mbcnt_hi_u32_b32 v1, s1, v1
	v_cmp_eq_u32_e32 vcc, 0, v1
	s_and_saveexec_b64 s[4:5], vcc
	s_cbranch_execz .LBB0_582
	s_bcnt1_i32_b64 s0, s[0:1]
	v_mov_b32_e32 v2, 0xc3000
	v_mov_b32_e32 v3, s0
	global_atomic_add v2, v2, v3, s[26:27] offset:1024 sc0

.LBB0_732:
	s_waitcnt vmcnt(0)
	s_setprio 0
	s_barrier
	s_mov_b64 s[6:7], exec
	v_readlane_b32 s0, v255, 4
	v_readlane_b32 s1, v255, 5
	v_readlane_b32 s88, v255, 20
	s_and_b64 s[0:1], s[6:7], s[0:1]
	v_readlane_b32 s89, v255, 21
	s_mov_b64 exec, s[0:1]
	s_cbranch_execz .LBB0_784
	s_add_i32 s0, 0, 0x25800
	v_mov_b32_e32 v0, s0
	s_waitcnt vmcnt(0) expcnt(0) lgkmcnt(0)
	buffer_inv sc1
	ds_read_b32 v2, v0
	s_add_i32 s0, 0, 0x25804
	v_mov_b32_e32 v0, s0
	ds_read_b32 v0, v0
	s_waitcnt lgkmcnt(1)
	v_cmp_ne_u32_e32 vcc, 0, v2
	s_cbranch_vccnz .LBB0_748
	s_add_u32 s8, s26, 0xc0200
	s_addc_u32 s9, s27, 0
	s_add_u32 s4, s26, 0xc0400
	s_addc_u32 s5, s27, 0
	s_add_u32 s10, s26, 0xc0500
	s_addc_u32 s11, s27, 0
	s_add_u32 s12, s26, 0xc0600
	s_addc_u32 s13, s27, 0
	s_add_u32 s14, s26, 0xc0700
	s_addc_u32 s15, s27, 0
	s_add_u32 s16, s26, 0xc0800
	s_addc_u32 s17, s27, 0
	s_add_u32 s18, s26, 0xc0900
	s_addc_u32 s19, s27, 0
	s_add_u32 s36, s26, 0xc0a00
	s_addc_u32 s37, s27, 0
	s_add_u32 s50, s26, 0xc0b00
	s_addc_u32 s51, s27, 0
	s_add_u32 s60, s26, 0xc0c00
	s_addc_u32 s61, s27, 0
	s_add_u32 s70, s26, 0xc0d00
	s_addc_u32 s71, s27, 0
	s_add_u32 s72, s26, 0xc0e00
	s_addc_u32 s73, s27, 0
	s_add_u32 s74, s26, 0xc0f00
	s_addc_u32 s75, s27, 0
	s_add_u32 s76, s26, 0xc1000
	s_addc_u32 s77, s27, 0
	s_add_u32 s78, s26, 0xc1100
	s_addc_u32 s79, s27, 0
	s_add_u32 s80, s26, 0xc1200
	v_readlane_b32 s0, v255, 0
	s_addc_u32 s81, s27, 0
	s_mul_i32 s20, s31, s0
	s_add_u32 s82, s26, 0xc1300
	s_mul_i32 s20, s20, s30
	s_addc_u32 s83, s27, 0
	s_mov_b32 s21, 1
	v_mov_b32_e32 v16, 0
	s_branch .LBB0_736

.LBB0_763:
	s_or_b64 exec, exec, s[0:1]
	s_waitcnt vmcnt(0)
.LBB0_764:
	s_andn2_saveexec_b64 s[0:1], s[4:5]
	s_cbranch_execz .LBB0_784
	s_mov_b64 s[0:1], exec
	buffer_wbl2 sc1
	s_waitcnt lgkmcnt(0)
	s_waitcnt vmcnt(0)
	v_mbcnt_lo_u32_b32 v1, s0, 0
	v_mbcnt_hi_u32_b32 v1, s1, v1
	v_cmp_eq_u32_e32 vcc, 0, v1
	s_and_saveexec_b64 s[4:5], vcc
	s_cbranch_execz .LBB0_767
	s_bcnt1_i32_b64 s0, s[0:1]
	v_mov_b32_e32 v2, 0xc3000
	v_mov_b32_e32 v3, s0
	global_atomic_add v2, v2, v3, s[26:27] offset:1024 sc0

.LBB0_787:
	s_waitcnt vmcnt(0)
	s_setprio 0
	s_barrier
	s_mov_b64 s[6:7], exec
	v_readlane_b32 s0, v255, 4
	v_readlane_b32 s1, v255, 5
	s_and_b64 s[0:1], s[6:7], s[0:1]
	s_mov_b64 exec, s[0:1]
	s_cbranch_execz .LBB0_839
	s_add_i32 s0, 0, 0x25800
	v_mov_b32_e32 v0, s0
	s_waitcnt vmcnt(0) expcnt(0) lgkmcnt(0)
	buffer_inv sc1
	ds_read_b32 v2, v0
	s_add_i32 s0, 0, 0x25804
	v_mov_b32_e32 v0, s0
	ds_read_b32 v0, v0
	s_waitcnt lgkmcnt(1)
	v_cmp_ne_u32_e32 vcc, 0, v2
	s_cbranch_vccnz .LBB0_803
	s_add_u32 s10, s26, 0xc0200
	s_addc_u32 s11, s27, 0
	s_add_u32 s4, s26, 0xc0400
	s_addc_u32 s5, s27, 0
	s_add_u32 s12, s26, 0xc0500
	s_addc_u32 s13, s27, 0
	s_add_u32 s14, s26, 0xc0600
	s_addc_u32 s15, s27, 0
	s_add_u32 s16, s26, 0xc0700
	s_addc_u32 s17, s27, 0
	s_add_u32 s18, s26, 0xc0800
	s_addc_u32 s19, s27, 0
	s_add_u32 s36, s26, 0xc0900
	s_addc_u32 s37, s27, 0
	s_add_u32 s48, s26, 0xc0a00
	s_addc_u32 s49, s27, 0
	s_add_u32 s50, s26, 0xc0b00
	s_addc_u32 s51, s27, 0
	s_add_u32 s52, s26, 0xc0c00
	s_addc_u32 s53, s27, 0
	s_add_u32 s56, s26, 0xc0d00
	s_addc_u32 s57, s27, 0
	s_add_u32 s60, s26, 0xc0e00
	s_addc_u32 s61, s27, 0
	s_add_u32 s66, s26, 0xc0f00
	s_addc_u32 s67, s27, 0
	s_add_u32 s68, s26, 0xc1000
	s_addc_u32 s69, s27, 0
	s_add_u32 s70, s26, 0xc1100
	s_addc_u32 s71, s27, 0
	s_add_u32 s72, s26, 0xc1200
	v_readlane_b32 s0, v255, 0
	s_addc_u32 s73, s27, 0
	s_mul_i32 s20, s31, s0
	s_add_u32 s74, s26, 0xc1300
	s_mul_i32 s20, s20, s30
	s_addc_u32 s75, s27, 0
	s_mov_b32 s21, 1
	v_mov_b32_e32 v16, 0
	s_branch .LBB0_791

.LBB0_818:
	s_or_b64 exec, exec, s[0:1]
	s_waitcnt vmcnt(0)
.LBB0_819:
	s_andn2_saveexec_b64 s[0:1], s[4:5]
	s_cbranch_execz .LBB0_839
	s_mov_b64 s[0:1], exec
	buffer_wbl2 sc1
	s_waitcnt lgkmcnt(0)
	s_waitcnt vmcnt(0)
	v_mbcnt_lo_u32_b32 v1, s0, 0
	v_mbcnt_hi_u32_b32 v1, s1, v1
	v_cmp_eq_u32_e32 vcc, 0, v1
	s_and_saveexec_b64 s[4:5], vcc
	s_cbranch_execz .LBB0_822
	s_bcnt1_i32_b64 s0, s[0:1]
	v_mov_b32_e32 v2, 0xc3000
	v_mov_b32_e32 v3, s0
	global_atomic_add v2, v2, v3, s[26:27] offset:1024 sc0

.LBB0_838:
	s_or_b64 exec, exec, s[4:5]
.LBB0_839:
	s_or_b64 exec, exec, s[6:7]
	s_waitcnt lgkmcnt(0)
	v_mov_b32_e32 v0, v254
	v_readlane_b32 s0, v255, 10
	s_barrier
	v_cmp_lt_u32_e32 vcc, 0xff, v254
	s_cbranch_vccz .Lprio_skip5
	s_setprio 1

.LBB0_855:
	s_waitcnt vmcnt(0)
	s_setprio 0
	s_barrier
	s_mov_b64 s[0:1], exec
	v_readlane_b32 s4, v255, 4
	v_readlane_b32 s5, v255, 5
	s_and_b64 s[4:5], s[0:1], s[4:5]
	s_xor_b64 s[6:7], s[4:5], s[0:1]
	s_mov_b64 exec, s[4:5]
	s_cbranch_execz .LBB0_908
	s_add_i32 s0, 0, 0x25800
	v_mov_b32_e32 v0, s0
	s_waitcnt vmcnt(0) expcnt(0) lgkmcnt(0)
	buffer_inv sc1
	ds_read_b32 v2, v0
	s_add_i32 s0, 0, 0x25804
	v_mov_b32_e32 v0, s0
	ds_read_b32 v0, v0
	s_waitcnt lgkmcnt(1)
	v_cmp_ne_u32_e32 vcc, 0, v2
	s_cbranch_vccnz .LBB0_871
	s_add_u32 s8, s26, 0xc0200
	s_addc_u32 s9, s27, 0
	s_add_u32 s4, s26, 0xc0400
	s_addc_u32 s5, s27, 0
	s_add_u32 s10, s26, 0xc0500
	s_addc_u32 s11, s27, 0
	s_add_u32 s12, s26, 0xc0600
	s_addc_u32 s13, s27, 0
	s_add_u32 s14, s26, 0xc0700
	s_addc_u32 s15, s27, 0
	s_add_u32 s16, s26, 0xc0800
	s_addc_u32 s17, s27, 0
	s_add_u32 s18, s26, 0xc0900
	s_addc_u32 s19, s27, 0
	s_add_u32 s36, s26, 0xc0a00
	s_addc_u32 s37, s27, 0
	s_add_u32 s48, s26, 0xc0b00
	s_addc_u32 s49, s27, 0
	s_add_u32 s50, s26, 0xc0c00
	s_addc_u32 s51, s27, 0
	s_add_u32 s52, s26, 0xc0d00
	s_addc_u32 s53, s27, 0
	s_add_u32 s56, s26, 0xc0e00
	s_addc_u32 s57, s27, 0
	s_add_u32 s60, s26, 0xc0f00
	s_addc_u32 s61, s27, 0
	s_add_u32 s64, s26, 0xc1000
	s_addc_u32 s65, s27, 0
	s_add_u32 s66, s26, 0xc1100
	s_addc_u32 s67, s27, 0
	s_add_u32 s68, s26, 0xc1200
	v_readlane_b32 s0, v255, 0
	s_addc_u32 s69, s27, 0
	s_mul_i32 s20, s31, s0
	s_add_u32 s70, s26, 0xc1300
	s_mul_i32 s20, s20, s30
	s_addc_u32 s71, s27, 0
	s_mov_b32 s21, 1
	v_mov_b32_e32 v16, 0
	s_branch .LBB0_859

.LBB0_886:
	s_or_b64 exec, exec, s[0:1]
	s_waitcnt vmcnt(0)
.LBB0_887:
	s_andn2_saveexec_b64 s[10:11], s[4:5]
	s_cbranch_execz .LBB0_907
	s_mov_b64 s[0:1], exec
	buffer_wbl2 sc1
	s_waitcnt lgkmcnt(0)
	s_waitcnt vmcnt(0)
	v_mbcnt_lo_u32_b32 v1, s0, 0
	v_mbcnt_hi_u32_b32 v1, s1, v1
	v_cmp_eq_u32_e32 vcc, 0, v1
	s_and_saveexec_b64 s[4:5], vcc
	s_cbranch_execz .LBB0_890
	s_bcnt1_i32_b64 s0, s[0:1]
	v_mov_b32_e32 v2, 0xc3000
	v_mov_b32_e32 v3, s0
	global_atomic_add v2, v2, v3, s[26:27] offset:1024 sc0

.LBB0_927:
	s_waitcnt vmcnt(0)
	s_setprio 0
	s_barrier
	s_mov_b64 s[6:7], exec
	v_readlane_b32 s0, v255, 4
	v_readlane_b32 s1, v255, 5
	s_and_b64 s[0:1], s[6:7], s[0:1]
	s_mov_b64 exec, s[0:1]
	s_cbranch_execz .LBB0_979
	s_add_i32 s0, 0, 0x25800
	v_mov_b32_e32 v0, s0
	s_waitcnt vmcnt(0) expcnt(0) lgkmcnt(0)
	buffer_inv sc1
	ds_read_b32 v2, v0
	s_add_i32 s0, 0, 0x25804
	v_mov_b32_e32 v0, s0
	ds_read_b32 v0, v0
	s_waitcnt lgkmcnt(1)
	v_cmp_ne_u32_e32 vcc, 0, v2
	s_cbranch_vccnz .LBB0_943
	s_add_u32 s8, s26, 0xc0200
	s_addc_u32 s9, s27, 0
	s_add_u32 s4, s26, 0xc0400
	s_addc_u32 s5, s27, 0
	s_add_u32 s10, s26, 0xc0500
	s_addc_u32 s11, s27, 0
	s_add_u32 s12, s26, 0xc0600
	s_addc_u32 s13, s27, 0
	s_add_u32 s14, s26, 0xc0700
	s_addc_u32 s15, s27, 0
	s_add_u32 s16, s26, 0xc0800
	s_addc_u32 s17, s27, 0
	s_add_u32 s18, s26, 0xc0900
	s_addc_u32 s19, s27, 0
	s_add_u32 s36, s26, 0xc0a00
	s_addc_u32 s37, s27, 0
	s_add_u32 s48, s26, 0xc0b00
	s_addc_u32 s49, s27, 0
	s_add_u32 s50, s26, 0xc0c00
	s_addc_u32 s51, s27, 0
	s_add_u32 s56, s26, 0xc0d00
	s_addc_u32 s57, s27, 0
	s_add_u32 s60, s26, 0xc0e00
	s_addc_u32 s61, s27, 0
	s_add_u32 s64, s26, 0xc0f00
	s_addc_u32 s65, s27, 0
	s_add_u32 s66, s26, 0xc1000
	s_addc_u32 s67, s27, 0
	s_add_u32 s68, s26, 0xc1100
	s_addc_u32 s69, s27, 0
	s_add_u32 s70, s26, 0xc1200
	v_readlane_b32 s0, v255, 0
	s_addc_u32 s71, s27, 0
	s_mul_i32 s20, s31, s0
	s_add_u32 s72, s26, 0xc1300
	s_mul_i32 s20, s20, s30
	s_addc_u32 s73, s27, 0
	s_mov_b32 s21, 1
	v_mov_b32_e32 v16, 0
	s_branch .LBB0_931

.LBB0_958:
	s_or_b64 exec, exec, s[0:1]
	s_waitcnt vmcnt(0)
.LBB0_959:
	s_andn2_saveexec_b64 s[0:1], s[4:5]
	s_cbranch_execz .LBB0_979
	s_mov_b64 s[0:1], exec
	buffer_wbl2 sc1
	s_waitcnt lgkmcnt(0)
	s_waitcnt vmcnt(0)
	v_mbcnt_lo_u32_b32 v1, s0, 0
	v_mbcnt_hi_u32_b32 v1, s1, v1
	v_cmp_eq_u32_e32 vcc, 0, v1
	s_and_saveexec_b64 s[4:5], vcc
	s_cbranch_execz .LBB0_962
	s_bcnt1_i32_b64 s0, s[0:1]
	v_mov_b32_e32 v2, 0xc3000
	v_mov_b32_e32 v3, s0
	global_atomic_add v2, v2, v3, s[26:27] offset:1024 sc0

.LBB0_978:
	s_or_b64 exec, exec, s[4:5]
.LBB0_979:
	s_or_b64 exec, exec, s[6:7]
	s_add_u32 s48, s26, 0x13200000
	s_addc_u32 s49, s27, 0
	s_cmpk_lt_i32 s2, 0x580
	s_cselect_b64 s[56:57], -1, 0
	v_mov_b32_e32 v128, v254
	v_mov_b32_e32 v9, v254
	s_waitcnt lgkmcnt(0)
	s_barrier
	v_cmp_lt_u32_e32 vcc, 0xff, v254
	s_cbranch_vccz .Lprio_skip7
	s_setprio 1

.LBB0_1030:
	s_waitcnt vmcnt(0)
	s_waitcnt vmcnt(0) lgkmcnt(0)
	s_setprio 0
	s_barrier
	s_mov_b64 s[0:1], exec
	v_readlane_b32 s4, v255, 4
	v_readlane_b32 s5, v255, 5
	s_and_b64 s[4:5], s[0:1], s[4:5]
	s_xor_b64 s[6:7], s[4:5], s[0:1]
	s_mov_b64 exec, s[4:5]
	s_cbranch_execz .LBB0_1083
	s_add_i32 s0, 0, 0x25800
	v_mov_b32_e32 v0, s0
	s_waitcnt vmcnt(0) expcnt(0) lgkmcnt(0)
	buffer_inv sc1
	ds_read_b32 v2, v0
	s_add_i32 s0, 0, 0x25804
	v_mov_b32_e32 v0, s0
	ds_read_b32 v0, v0
	s_waitcnt lgkmcnt(1)
	v_cmp_ne_u32_e32 vcc, 0, v2
	s_cbranch_vccnz .LBB0_1046
	s_add_u32 s8, s26, 0xc0200
	s_addc_u32 s9, s27, 0
	s_add_u32 s4, s26, 0xc0400
	s_addc_u32 s5, s27, 0
	s_add_u32 s10, s26, 0xc0500
	s_addc_u32 s11, s27, 0
	s_add_u32 s12, s26, 0xc0600
	s_addc_u32 s13, s27, 0
	s_add_u32 s14, s26, 0xc0700
	s_addc_u32 s15, s27, 0
	s_add_u32 s16, s26, 0xc0800
	s_addc_u32 s17, s27, 0
	s_add_u32 s18, s26, 0xc0900
	s_addc_u32 s19, s27, 0
	s_add_u32 s20, s26, 0xc0a00
	s_addc_u32 s21, s27, 0
	s_add_u32 s36, s26, 0xc0b00
	s_addc_u32 s37, s27, 0
	s_add_u32 s46, s26, 0xc0c00
	s_addc_u32 s47, s27, 0
	s_add_u32 s60, s26, 0xc0d00
	s_addc_u32 s61, s27, 0
	s_add_u32 s62, s26, 0xc0e00
	s_addc_u32 s63, s27, 0
	s_add_u32 s64, s26, 0xc0f00
	s_addc_u32 s65, s27, 0
	s_add_u32 s66, s26, 0xc1000
	s_addc_u32 s67, s27, 0
	s_add_u32 s68, s26, 0xc1100
	s_addc_u32 s69, s27, 0
	s_add_u32 s70, s26, 0xc1200
	v_readlane_b32 s0, v255, 0
	s_addc_u32 s71, s27, 0
	s_mul_i32 s23, s31, s0
	s_add_u32 s72, s26, 0xc1300
	s_mul_i32 s23, s23, s30
	s_addc_u32 s73, s27, 0
	s_mov_b32 s24, 1
	v_mov_b32_e32 v16, 0
	s_branch .LBB0_1034

.LBB0_1061:
	s_or_b64 exec, exec, s[0:1]
	s_waitcnt vmcnt(0)
.LBB0_1062:
	s_andn2_saveexec_b64 s[10:11], s[4:5]
	s_cbranch_execz .LBB0_1082
	s_mov_b64 s[0:1], exec
	buffer_wbl2 sc1
	s_waitcnt lgkmcnt(0)
	s_waitcnt vmcnt(0)
	v_mbcnt_lo_u32_b32 v1, s0, 0
	v_mbcnt_hi_u32_b32 v1, s1, v1
	v_cmp_eq_u32_e32 vcc, 0, v1
	s_and_saveexec_b64 s[4:5], vcc
	s_cbranch_execz .LBB0_1065
	s_bcnt1_i32_b64 s0, s[0:1]
	v_mov_b32_e32 v2, 0xc3000
	v_mov_b32_e32 v3, s0
	global_atomic_add v2, v2, v3, s[26:27] offset:1024 sc0

.LBB0_1103:
	s_waitcnt vmcnt(0)
	s_waitcnt lgkmcnt(0)
	s_setprio 0
	s_barrier
	s_mov_b64 s[0:1], exec
	v_readlane_b32 s4, v255, 4
	v_readlane_b32 s5, v255, 5
	s_and_b64 s[4:5], s[0:1], s[4:5]
	v_readlane_b32 s40, v255, 10
	s_xor_b64 s[6:7], s[4:5], s[0:1]
	v_readlane_b32 s41, v255, 11
	s_mov_b64 exec, s[4:5]
	s_cbranch_execz .LBB0_1156
	s_add_i32 s0, 0, 0x25800
	v_mov_b32_e32 v0, s0
	s_waitcnt vmcnt(0) expcnt(0) lgkmcnt(0)
	buffer_inv sc1
	ds_read_b32 v2, v0
	s_add_i32 s0, 0, 0x25804
	v_mov_b32_e32 v0, s0
	ds_read_b32 v0, v0
	s_waitcnt lgkmcnt(1)
	v_cmp_ne_u32_e32 vcc, 0, v2
	s_cbranch_vccnz .LBB0_1119
	s_add_u32 s8, s26, 0xc0200
	s_addc_u32 s9, s27, 0
	s_add_u32 s4, s26, 0xc0400
	s_addc_u32 s5, s27, 0
	s_add_u32 s10, s26, 0xc0500
	s_addc_u32 s11, s27, 0
	s_add_u32 s12, s26, 0xc0600
	s_addc_u32 s13, s27, 0
	s_add_u32 s14, s26, 0xc0700
	s_addc_u32 s15, s27, 0
	s_add_u32 s16, s26, 0xc0800
	s_addc_u32 s17, s27, 0
	s_add_u32 s18, s26, 0xc0900
	s_addc_u32 s19, s27, 0
	s_add_u32 s20, s26, 0xc0a00
	s_addc_u32 s21, s27, 0
	s_add_u32 s36, s26, 0xc0b00
	s_addc_u32 s37, s27, 0
	s_add_u32 s46, s26, 0xc0c00
	s_addc_u32 s47, s27, 0
	s_add_u32 s58, s26, 0xc0d00
	s_addc_u32 s59, s27, 0
	s_add_u32 s60, s26, 0xc0e00
	s_addc_u32 s61, s27, 0
	s_add_u32 s62, s26, 0xc0f00
	s_addc_u32 s63, s27, 0
	s_add_u32 s64, s26, 0xc1000
	s_addc_u32 s65, s27, 0
	s_add_u32 s66, s26, 0xc1100
	s_addc_u32 s67, s27, 0
	s_add_u32 s68, s26, 0xc1200
	v_readlane_b32 s0, v255, 0
	s_addc_u32 s69, s27, 0
	s_mul_i32 s23, s31, s0
	s_add_u32 s70, s26, 0xc1300
	s_mul_i32 s23, s23, s30
	s_addc_u32 s71, s27, 0
	s_mov_b32 s24, 1
	v_mov_b32_e32 v16, 0
	s_branch .LBB0_1107

.LBB0_1134:
	s_or_b64 exec, exec, s[0:1]
	s_waitcnt vmcnt(0)
.LBB0_1135:
	s_andn2_saveexec_b64 s[10:11], s[4:5]
	s_cbranch_execz .LBB0_1155
	s_mov_b64 s[0:1], exec
	buffer_wbl2 sc1
	s_waitcnt lgkmcnt(0)
	s_waitcnt vmcnt(0)
	v_mbcnt_lo_u32_b32 v1, s0, 0
	v_mbcnt_hi_u32_b32 v1, s1, v1
	v_cmp_eq_u32_e32 vcc, 0, v1
	s_and_saveexec_b64 s[4:5], vcc
	s_cbranch_execz .LBB0_1138
	s_bcnt1_i32_b64 s0, s[0:1]
	v_mov_b32_e32 v2, 0xc3000
	v_mov_b32_e32 v3, s0
	global_atomic_add v2, v2, v3, s[26:27] offset:1024 sc0

.LBB0_1175:
	s_waitcnt vmcnt(0)
	s_setprio 0
	s_barrier
	s_mov_b64 s[6:7], exec
	v_readlane_b32 s0, v255, 4
	v_readlane_b32 s1, v255, 5
	s_and_b64 s[0:1], s[6:7], s[0:1]
	s_mov_b64 exec, s[0:1]
	s_cbranch_execz .LBB0_1227
	s_add_i32 s0, 0, 0x25800
	v_mov_b32_e32 v0, s0
	s_waitcnt vmcnt(0) expcnt(0) lgkmcnt(0)
	buffer_inv sc1
	ds_read_b32 v2, v0
	s_add_i32 s0, 0, 0x25804
	v_mov_b32_e32 v0, s0
	ds_read_b32 v0, v0
	s_waitcnt lgkmcnt(1)
	v_cmp_ne_u32_e32 vcc, 0, v2
	s_cbranch_vccnz .LBB0_1191
	s_add_u32 s8, s26, 0xc0200
	s_addc_u32 s9, s27, 0
	s_add_u32 s4, s26, 0xc0400
	s_addc_u32 s5, s27, 0
	s_add_u32 s10, s26, 0xc0500
	s_addc_u32 s11, s27, 0
	s_add_u32 s12, s26, 0xc0600
	s_addc_u32 s13, s27, 0
	s_add_u32 s14, s26, 0xc0700
	s_addc_u32 s15, s27, 0
	s_add_u32 s16, s26, 0xc0800
	s_addc_u32 s17, s27, 0
	s_add_u32 s18, s26, 0xc0900
	s_addc_u32 s19, s27, 0
	s_add_u32 s20, s26, 0xc0a00
	s_addc_u32 s21, s27, 0
	s_add_u32 s36, s26, 0xc0b00
	s_addc_u32 s37, s27, 0
	s_add_u32 s46, s26, 0xc0c00
	s_addc_u32 s47, s27, 0
	s_add_u32 s58, s26, 0xc0d00
	s_addc_u32 s59, s27, 0
	s_add_u32 s60, s26, 0xc0e00
	s_addc_u32 s61, s27, 0
	s_add_u32 s62, s26, 0xc0f00
	s_addc_u32 s63, s27, 0
	s_add_u32 s64, s26, 0xc1000
	s_addc_u32 s65, s27, 0
	s_add_u32 s66, s26, 0xc1100
	s_addc_u32 s67, s27, 0
	s_add_u32 s68, s26, 0xc1200
	v_readlane_b32 s0, v255, 0
	s_addc_u32 s69, s27, 0
	s_mul_i32 s23, s31, s0
	s_add_u32 s70, s26, 0xc1300
	s_mul_i32 s23, s23, s30
	s_addc_u32 s71, s27, 0
	s_mov_b32 s24, 1
	v_mov_b32_e32 v16, 0
	s_branch .LBB0_1179

.LBB0_1206:
	s_or_b64 exec, exec, s[0:1]
	s_waitcnt vmcnt(0)
.LBB0_1207:
	s_andn2_saveexec_b64 s[0:1], s[4:5]
	s_cbranch_execz .LBB0_1227
	s_mov_b64 s[0:1], exec
	buffer_wbl2 sc1
	s_waitcnt lgkmcnt(0)
	s_waitcnt vmcnt(0)
	v_mbcnt_lo_u32_b32 v1, s0, 0
	v_mbcnt_hi_u32_b32 v1, s1, v1
	v_cmp_eq_u32_e32 vcc, 0, v1
	s_and_saveexec_b64 s[4:5], vcc
	s_cbranch_execz .LBB0_1210
	s_bcnt1_i32_b64 s0, s[0:1]
	v_mov_b32_e32 v2, 0xc3000
	v_mov_b32_e32 v3, s0
	global_atomic_add v2, v2, v3, s[26:27] offset:1024 sc0

.LBB0_1226:
	s_or_b64 exec, exec, s[4:5]
.LBB0_1227:
	s_or_b64 exec, exec, s[6:7]
	s_waitcnt lgkmcnt(0)
	v_mov_b32_e32 v0, v254
	s_barrier
	v_cmp_lt_u32_e32 vcc, 0xff, v254
	s_cbranch_vccz .Lprio_skip10
	s_setprio 1

.LBB0_1239:
	s_waitcnt vmcnt(0)
	s_setprio 0
	s_barrier
	s_mov_b64 s[0:1], exec
	v_readlane_b32 s4, v255, 4
	v_readlane_b32 s5, v255, 5
	s_and_b64 s[4:5], s[0:1], s[4:5]
	s_xor_b64 s[6:7], s[4:5], s[0:1]
	s_mov_b64 exec, s[4:5]
	s_cbranch_execz .LBB0_1292
	s_add_i32 s0, 0, 0x25800
	v_mov_b32_e32 v0, s0
	s_waitcnt vmcnt(0) expcnt(0) lgkmcnt(0)
	buffer_inv sc1
	ds_read_b32 v2, v0
	s_add_i32 s0, 0, 0x25804
	v_mov_b32_e32 v0, s0
	ds_read_b32 v0, v0
	s_waitcnt lgkmcnt(1)
	v_cmp_ne_u32_e32 vcc, 0, v2
	s_cbranch_vccnz .LBB0_1255
	s_add_u32 s8, s26, 0xc0200
	s_addc_u32 s9, s27, 0
	s_add_u32 s4, s26, 0xc0400
	s_addc_u32 s5, s27, 0
	s_add_u32 s10, s26, 0xc0500
	s_addc_u32 s11, s27, 0
	s_add_u32 s12, s26, 0xc0600
	s_addc_u32 s13, s27, 0
	s_add_u32 s14, s26, 0xc0700
	s_addc_u32 s15, s27, 0
	s_add_u32 s16, s26, 0xc0800
	s_addc_u32 s17, s27, 0
	s_add_u32 s18, s26, 0xc0900
	s_addc_u32 s19, s27, 0
	s_add_u32 s20, s26, 0xc0a00
	s_addc_u32 s21, s27, 0
	s_add_u32 s36, s26, 0xc0b00
	s_addc_u32 s37, s27, 0
	s_add_u32 s46, s26, 0xc0c00
	s_addc_u32 s47, s27, 0
	s_add_u32 s54, s26, 0xc0d00
	s_addc_u32 s55, s27, 0
	s_add_u32 s58, s26, 0xc0e00
	s_addc_u32 s59, s27, 0
	s_add_u32 s60, s26, 0xc0f00
	s_addc_u32 s61, s27, 0
	s_add_u32 s62, s26, 0xc1000
	s_addc_u32 s63, s27, 0
	s_add_u32 s64, s26, 0xc1100
	s_addc_u32 s65, s27, 0
	s_add_u32 s66, s26, 0xc1200
	v_readlane_b32 s0, v255, 0
	s_addc_u32 s67, s27, 0
	s_mul_i32 s23, s31, s0
	s_add_u32 s68, s26, 0xc1300
	s_mul_i32 s23, s23, s30
	s_addc_u32 s69, s27, 0
	s_mov_b32 s24, 1
	v_mov_b32_e32 v16, 0
	s_branch .LBB0_1243

.LBB0_1270:
	s_or_b64 exec, exec, s[0:1]
	s_waitcnt vmcnt(0)
.LBB0_1271:
	s_andn2_saveexec_b64 s[10:11], s[4:5]
	s_cbranch_execz .LBB0_1291
	s_mov_b64 s[0:1], exec
	buffer_wbl2 sc1
	s_waitcnt lgkmcnt(0)
	s_waitcnt vmcnt(0)
	v_mbcnt_lo_u32_b32 v1, s0, 0
	v_mbcnt_hi_u32_b32 v1, s1, v1
	v_cmp_eq_u32_e32 vcc, 0, v1
	s_and_saveexec_b64 s[4:5], vcc
	s_cbranch_execz .LBB0_1274
	s_bcnt1_i32_b64 s0, s[0:1]
	v_mov_b32_e32 v2, 0xc3000
	v_mov_b32_e32 v3, s0
	global_atomic_add v2, v2, v3, s[26:27] offset:1024 sc0

.LBB0_1319:
	s_waitcnt vmcnt(0)
	s_setprio 0
	s_barrier
	s_mov_b64 s[6:7], exec
	v_readlane_b32 s0, v255, 4
	v_readlane_b32 s1, v255, 5
	s_and_b64 s[0:1], s[6:7], s[0:1]
	s_mov_b64 exec, s[0:1]
	s_cbranch_execz .LBB0_1371
	s_add_i32 s0, 0, 0x25800
	v_mov_b32_e32 v0, s0
	s_waitcnt vmcnt(0) expcnt(0) lgkmcnt(0)
	buffer_inv sc1
	ds_read_b32 v2, v0
	s_add_i32 s0, 0, 0x25804
	v_mov_b32_e32 v0, s0
	ds_read_b32 v0, v0
	s_waitcnt lgkmcnt(1)
	v_cmp_ne_u32_e32 vcc, 0, v2
	s_cbranch_vccnz .LBB0_1335
	s_add_u32 s8, s26, 0xc0200
	s_addc_u32 s9, s27, 0
	s_add_u32 s4, s26, 0xc0400
	s_addc_u32 s5, s27, 0
	s_add_u32 s10, s26, 0xc0500
	s_addc_u32 s11, s27, 0
	s_add_u32 s12, s26, 0xc0600
	s_addc_u32 s13, s27, 0
	s_add_u32 s14, s26, 0xc0700
	s_addc_u32 s15, s27, 0
	s_add_u32 s16, s26, 0xc0800
	s_addc_u32 s17, s27, 0
	s_add_u32 s18, s26, 0xc0900
	s_addc_u32 s19, s27, 0
	s_add_u32 s20, s26, 0xc0a00
	s_addc_u32 s21, s27, 0
	s_add_u32 s36, s26, 0xc0b00
	s_addc_u32 s37, s27, 0
	s_add_u32 s58, s26, 0xc0c00
	s_addc_u32 s59, s27, 0
	s_add_u32 s60, s26, 0xc0d00
	s_addc_u32 s61, s27, 0
	s_add_u32 s62, s26, 0xc0e00
	s_addc_u32 s63, s27, 0
	s_add_u32 s64, s26, 0xc0f00
	s_addc_u32 s65, s27, 0
	s_add_u32 s66, s26, 0xc1000
	s_addc_u32 s67, s27, 0
	s_add_u32 s68, s26, 0xc1100
	s_addc_u32 s69, s27, 0
	s_add_u32 s70, s26, 0xc1200
	v_readlane_b32 s0, v255, 0
	s_addc_u32 s71, s27, 0
	s_mul_i32 s23, s31, s0
	s_add_u32 s72, s26, 0xc1300
	s_mul_i32 s23, s23, s30
	s_addc_u32 s73, s27, 0
	s_mov_b32 s24, 1
	v_mov_b32_e32 v16, 0
	s_branch .LBB0_1323

.LBB0_1350:
	s_or_b64 exec, exec, s[0:1]
	s_waitcnt vmcnt(0)
.LBB0_1351:
	s_andn2_saveexec_b64 s[0:1], s[4:5]
	s_cbranch_execz .LBB0_1371
	s_mov_b64 s[0:1], exec
	buffer_wbl2 sc1
	s_waitcnt lgkmcnt(0)
	s_waitcnt vmcnt(0)
	v_mbcnt_lo_u32_b32 v1, s0, 0
	v_mbcnt_hi_u32_b32 v1, s1, v1
	v_cmp_eq_u32_e32 vcc, 0, v1
	s_and_saveexec_b64 s[4:5], vcc
	s_cbranch_execz .LBB0_1354
	s_bcnt1_i32_b64 s0, s[0:1]
	v_mov_b32_e32 v2, 0xc3000
	v_mov_b32_e32 v3, s0
	global_atomic_add v2, v2, v3, s[26:27] offset:1024 sc0

.LBB0_1413:
	s_waitcnt vmcnt(0)
	s_setprio 0
	s_barrier
	s_mov_b64 s[0:1], exec
	v_readlane_b32 s4, v255, 4
	v_readlane_b32 s5, v255, 5
	s_and_b64 s[4:5], s[0:1], s[4:5]
	s_xor_b64 s[6:7], s[4:5], s[0:1]
	s_mov_b64 exec, s[4:5]
	s_cbranch_execz .LBB0_1466
	s_add_i32 s0, 0, 0x25800
	v_mov_b32_e32 v0, s0
	s_waitcnt vmcnt(0) expcnt(0) lgkmcnt(0)
	buffer_inv sc1
	ds_read_b32 v2, v0
	s_add_i32 s0, 0, 0x25804
	v_mov_b32_e32 v0, s0
	ds_read_b32 v0, v0
	s_waitcnt lgkmcnt(1)
	v_cmp_ne_u32_e32 vcc, 0, v2
	s_cbranch_vccnz .LBB0_1429
	s_add_u32 s8, s26, 0xc0200
	s_addc_u32 s9, s27, 0
	s_add_u32 s4, s26, 0xc0400
	s_addc_u32 s5, s27, 0
	s_add_u32 s10, s26, 0xc0500
	s_addc_u32 s11, s27, 0
	s_add_u32 s12, s26, 0xc0600
	s_addc_u32 s13, s27, 0
	s_add_u32 s14, s26, 0xc0700
	s_addc_u32 s15, s27, 0
	s_add_u32 s16, s26, 0xc0800
	s_addc_u32 s17, s27, 0
	s_add_u32 s18, s26, 0xc0900
	s_addc_u32 s19, s27, 0
	s_add_u32 s20, s26, 0xc0a00
	s_addc_u32 s21, s27, 0
	s_add_u32 s36, s26, 0xc0b00
	s_addc_u32 s37, s27, 0
	s_add_u32 s46, s26, 0xc0c00
	s_addc_u32 s47, s27, 0
	s_add_u32 s50, s26, 0xc0d00
	s_addc_u32 s51, s27, 0
	s_add_u32 s54, s26, 0xc0e00
	s_addc_u32 s55, s27, 0
	s_add_u32 s58, s26, 0xc0f00
	s_addc_u32 s59, s27, 0
	s_add_u32 s60, s26, 0xc1000
	s_addc_u32 s61, s27, 0
	s_add_u32 s62, s26, 0xc1100
	s_addc_u32 s63, s27, 0
	s_add_u32 s64, s26, 0xc1200
	v_readlane_b32 s0, v255, 0
	s_addc_u32 s65, s27, 0
	s_mul_i32 s23, s31, s0
	s_add_u32 s66, s26, 0xc1300
	s_mul_i32 s23, s23, s30
	s_addc_u32 s67, s27, 0
	s_mov_b32 s24, 1
	v_mov_b32_e32 v16, 0
	s_branch .LBB0_1417

.LBB0_1444:
	s_or_b64 exec, exec, s[0:1]
	s_waitcnt vmcnt(0)
.LBB0_1445:
	s_andn2_saveexec_b64 s[10:11], s[4:5]
	s_cbranch_execz .LBB0_1465
	s_mov_b64 s[0:1], exec
	buffer_wbl2 sc1
	s_waitcnt lgkmcnt(0)
	s_waitcnt vmcnt(0)
	v_mbcnt_lo_u32_b32 v1, s0, 0
	v_mbcnt_hi_u32_b32 v1, s1, v1
	v_cmp_eq_u32_e32 vcc, 0, v1
	s_and_saveexec_b64 s[4:5], vcc
	s_cbranch_execz .LBB0_1448
	s_bcnt1_i32_b64 s0, s[0:1]
	v_mov_b32_e32 v2, 0xc3000
	v_mov_b32_e32 v3, s0
	global_atomic_add v2, v2, v3, s[26:27] offset:1024 sc0

.LBB0_1469:
	s_waitcnt vmcnt(0)
	s_setprio 0
	s_barrier
	s_mov_b64 s[6:7], exec
	v_readlane_b32 s0, v255, 4
	v_readlane_b32 s1, v255, 5
	s_and_b64 s[0:1], s[6:7], s[0:1]
	s_mov_b64 exec, s[0:1]
	s_cbranch_execz .LBB0_1521
	s_add_i32 s0, 0, 0x25800
	v_mov_b32_e32 v0, s0
	s_waitcnt vmcnt(0) expcnt(0) lgkmcnt(0)
	buffer_inv sc1
	ds_read_b32 v2, v0
	s_add_i32 s0, 0, 0x25804
	v_mov_b32_e32 v0, s0
	ds_read_b32 v0, v0
	s_waitcnt lgkmcnt(1)
	v_cmp_ne_u32_e32 vcc, 0, v2
	s_cbranch_vccnz .LBB0_1485
	s_add_u32 s8, s26, 0xc0200
	s_addc_u32 s9, s27, 0
	s_add_u32 s4, s26, 0xc0400
	s_addc_u32 s5, s27, 0
	s_add_u32 s10, s26, 0xc0500
	s_addc_u32 s11, s27, 0
	s_add_u32 s12, s26, 0xc0600
	s_addc_u32 s13, s27, 0
	s_add_u32 s14, s26, 0xc0700
	s_addc_u32 s15, s27, 0
	s_add_u32 s16, s26, 0xc0800
	s_addc_u32 s17, s27, 0
	s_add_u32 s18, s26, 0xc0900
	s_addc_u32 s19, s27, 0
	s_add_u32 s20, s26, 0xc0a00
	s_addc_u32 s21, s27, 0
	s_add_u32 s36, s26, 0xc0b00
	s_addc_u32 s37, s27, 0
	s_add_u32 s46, s26, 0xc0c00
	s_addc_u32 s47, s27, 0
	s_add_u32 s50, s26, 0xc0d00
	s_addc_u32 s51, s27, 0
	s_add_u32 s54, s26, 0xc0e00
	s_addc_u32 s55, s27, 0
	s_add_u32 s58, s26, 0xc0f00
	s_addc_u32 s59, s27, 0
	s_add_u32 s60, s26, 0xc1000
	s_addc_u32 s61, s27, 0
	s_add_u32 s62, s26, 0xc1100
	s_addc_u32 s63, s27, 0
	s_add_u32 s64, s26, 0xc1200
	v_readlane_b32 s0, v255, 0
	s_addc_u32 s65, s27, 0
	s_mul_i32 s23, s31, s0
	s_add_u32 s66, s26, 0xc1300
	s_mul_i32 s23, s23, s30
	s_addc_u32 s67, s27, 0
	s_mov_b32 s24, 1
	v_mov_b32_e32 v16, 0
	s_branch .LBB0_1473

.LBB0_1500:
	s_or_b64 exec, exec, s[0:1]
	s_waitcnt vmcnt(0)
.LBB0_1501:
	s_andn2_saveexec_b64 s[0:1], s[4:5]
	s_cbranch_execz .LBB0_1521
	s_mov_b64 s[0:1], exec
	buffer_wbl2 sc1
	s_waitcnt lgkmcnt(0)
	s_waitcnt vmcnt(0)
	v_mbcnt_lo_u32_b32 v1, s0, 0
	v_mbcnt_hi_u32_b32 v1, s1, v1
	v_cmp_eq_u32_e32 vcc, 0, v1
	s_and_saveexec_b64 s[4:5], vcc
	s_cbranch_execz .LBB0_1504
	s_bcnt1_i32_b64 s0, s[0:1]
	v_mov_b32_e32 v2, 0xc3000
	v_mov_b32_e32 v3, s0
	global_atomic_add v2, v2, v3, s[26:27] offset:1024 sc0

.LBB0_1520:
	s_or_b64 exec, exec, s[4:5]
.LBB0_1521:
	s_or_b64 exec, exec, s[6:7]
	s_waitcnt lgkmcnt(0)
	v_mov_b32_e32 v0, v254
	s_barrier
	v_cmp_lt_u32_e32 vcc, 0xff, v254
	s_cbranch_vccz .Lprio_skip14
	s_setprio 1

.LBB0_1545:
	s_waitcnt vmcnt(0)
	s_setprio 0
	s_barrier
	s_mov_b64 s[0:1], exec
	v_readlane_b32 s4, v255, 4
	v_readlane_b32 s5, v255, 5
	s_and_b64 s[4:5], s[0:1], s[4:5]
	s_xor_b64 s[6:7], s[4:5], s[0:1]
	s_mov_b64 exec, s[4:5]
	s_cbranch_execz .LBB0_1598
	s_add_i32 s0, 0, 0x25800
	v_mov_b32_e32 v0, s0
	s_waitcnt vmcnt(0) expcnt(0) lgkmcnt(0)
	buffer_inv sc1
	ds_read_b32 v2, v0
	s_add_i32 s0, 0, 0x25804
	v_mov_b32_e32 v0, s0
	ds_read_b32 v0, v0
	s_waitcnt lgkmcnt(1)
	v_cmp_ne_u32_e32 vcc, 0, v2
	s_cbranch_vccnz .LBB0_1561
	s_add_u32 s8, s26, 0xc0200
	s_addc_u32 s9, s27, 0
	s_add_u32 s4, s26, 0xc0400
	s_addc_u32 s5, s27, 0
	s_add_u32 s10, s26, 0xc0500
	s_addc_u32 s11, s27, 0
	s_add_u32 s12, s26, 0xc0600
	s_addc_u32 s13, s27, 0
	s_add_u32 s14, s26, 0xc0700
	s_addc_u32 s15, s27, 0
	s_add_u32 s16, s26, 0xc0800
	s_addc_u32 s17, s27, 0
	s_add_u32 s18, s26, 0xc0900
	s_addc_u32 s19, s27, 0
	s_add_u32 s20, s26, 0xc0a00
	s_addc_u32 s21, s27, 0
	s_add_u32 s36, s26, 0xc0b00
	s_addc_u32 s37, s27, 0
	s_add_u32 s44, s26, 0xc0c00
	s_addc_u32 s45, s27, 0
	s_add_u32 s46, s26, 0xc0d00
	s_addc_u32 s47, s27, 0
	s_add_u32 s50, s26, 0xc0e00
	s_addc_u32 s51, s27, 0
	s_add_u32 s54, s26, 0xc0f00
	s_addc_u32 s55, s27, 0
	s_add_u32 s58, s26, 0xc1000
	s_addc_u32 s59, s27, 0
	s_add_u32 s60, s26, 0xc1100
	s_addc_u32 s61, s27, 0
	s_add_u32 s62, s26, 0xc1200
	v_readlane_b32 s0, v255, 0
	s_addc_u32 s63, s27, 0
	s_mul_i32 s23, s31, s0
	s_add_u32 s64, s26, 0xc1300
	s_mul_i32 s23, s23, s30
	s_addc_u32 s65, s27, 0
	s_mov_b32 s24, 1
	v_mov_b32_e32 v16, 0
	s_branch .LBB0_1549

.LBB0_1576:
	s_or_b64 exec, exec, s[0:1]
	s_waitcnt vmcnt(0)
.LBB0_1577:
	s_andn2_saveexec_b64 s[10:11], s[4:5]
	s_cbranch_execz .LBB0_1597
	s_mov_b64 s[0:1], exec
	buffer_wbl2 sc1
	s_waitcnt lgkmcnt(0)
	s_waitcnt vmcnt(0)
	v_mbcnt_lo_u32_b32 v1, s0, 0
	v_mbcnt_hi_u32_b32 v1, s1, v1
	v_cmp_eq_u32_e32 vcc, 0, v1
	s_and_saveexec_b64 s[4:5], vcc
	s_cbranch_execz .LBB0_1580
	s_bcnt1_i32_b64 s0, s[0:1]
	v_mov_b32_e32 v2, 0xc3000
	v_mov_b32_e32 v3, s0
	global_atomic_add v2, v2, v3, s[26:27] offset:1024 sc0

.LBB0_1617:
	s_waitcnt vmcnt(0)
	s_setprio 0
	s_barrier
	s_mov_b64 s[6:7], exec
	v_readlane_b32 s0, v255, 4
	v_readlane_b32 s1, v255, 5
	s_and_b64 s[0:1], s[6:7], s[0:1]
	s_mov_b64 exec, s[0:1]
	s_cbranch_execz .LBB0_1669
	s_add_i32 s0, 0, 0x25800
	v_mov_b32_e32 v0, s0
	s_waitcnt vmcnt(0) expcnt(0) lgkmcnt(0)
	buffer_inv sc1
	ds_read_b32 v2, v0
	s_add_i32 s0, 0, 0x25804
	v_mov_b32_e32 v0, s0
	ds_read_b32 v0, v0
	s_waitcnt lgkmcnt(1)
	v_cmp_ne_u32_e32 vcc, 0, v2
	s_cbranch_vccnz .LBB0_1633
	s_add_u32 s8, s26, 0xc0200
	s_addc_u32 s9, s27, 0
	s_add_u32 s4, s26, 0xc0400
	s_addc_u32 s5, s27, 0
	s_add_u32 s10, s26, 0xc0500
	s_addc_u32 s11, s27, 0
	s_add_u32 s12, s26, 0xc0600
	s_addc_u32 s13, s27, 0
	s_add_u32 s14, s26, 0xc0700
	s_addc_u32 s15, s27, 0
	s_add_u32 s16, s26, 0xc0800
	s_addc_u32 s17, s27, 0
	s_add_u32 s18, s26, 0xc0900
	s_addc_u32 s19, s27, 0
	s_add_u32 s20, s26, 0xc0a00
	s_addc_u32 s21, s27, 0
	s_add_u32 s36, s26, 0xc0b00
	s_addc_u32 s37, s27, 0
	s_add_u32 s44, s26, 0xc0c00
	s_addc_u32 s45, s27, 0
	s_add_u32 s46, s26, 0xc0d00
	s_addc_u32 s47, s27, 0
	s_add_u32 s50, s26, 0xc0e00
	s_addc_u32 s51, s27, 0
	s_add_u32 s52, s26, 0xc0f00
	s_addc_u32 s53, s27, 0
	s_add_u32 s54, s26, 0xc1000
	s_addc_u32 s55, s27, 0
	s_add_u32 s58, s26, 0xc1100
	s_addc_u32 s59, s27, 0
	s_add_u32 s60, s26, 0xc1200
	v_readlane_b32 s0, v255, 0
	s_addc_u32 s61, s27, 0
	s_mul_i32 s23, s31, s0
	s_add_u32 s62, s26, 0xc1300
	s_mul_i32 s23, s23, s30
	s_addc_u32 s63, s27, 0
	s_mov_b32 s24, 1
	v_mov_b32_e32 v16, 0
	s_branch .LBB0_1621

.LBB0_1648:
	s_or_b64 exec, exec, s[0:1]
	s_waitcnt vmcnt(0)
.LBB0_1649:
	s_andn2_saveexec_b64 s[0:1], s[4:5]
	s_cbranch_execz .LBB0_1669
	s_mov_b64 s[0:1], exec
	buffer_wbl2 sc1
	s_waitcnt lgkmcnt(0)
	s_waitcnt vmcnt(0)
	v_mbcnt_lo_u32_b32 v1, s0, 0
	v_mbcnt_hi_u32_b32 v1, s1, v1
	v_cmp_eq_u32_e32 vcc, 0, v1
	s_and_saveexec_b64 s[4:5], vcc
	s_cbranch_execz .LBB0_1652
	s_bcnt1_i32_b64 s0, s[0:1]
	v_mov_b32_e32 v2, 0xc3000
	v_mov_b32_e32 v3, s0
	global_atomic_add v2, v2, v3, s[26:27] offset:1024 sc0

.LBB0_1668:
	s_or_b64 exec, exec, s[4:5]
.LBB0_1669:
	s_or_b64 exec, exec, s[6:7]
	s_waitcnt lgkmcnt(0)
	v_mov_b32_e32 v0, v254
	v_mov_b32_e32 v9, v254
	s_barrier
	v_cmp_lt_u32_e32 vcc, 0xff, v254
	s_cbranch_vccz .Lprio_skip16
	s_setprio 1

.LBB0_1681:
	s_waitcnt vmcnt(0)
	s_waitcnt vmcnt(0) lgkmcnt(0)
	s_setprio 0
	s_barrier
	s_mov_b64 s[0:1], exec
	v_readlane_b32 s4, v255, 4
	v_readlane_b32 s5, v255, 5
	s_and_b64 s[4:5], s[0:1], s[4:5]
	s_xor_b64 s[6:7], s[4:5], s[0:1]
	s_mov_b64 exec, s[4:5]
	s_cbranch_execz .LBB0_1734
	s_add_i32 s0, 0, 0x25800
	v_mov_b32_e32 v0, s0
	s_waitcnt vmcnt(0) expcnt(0) lgkmcnt(0)
	buffer_inv sc1
	ds_read_b32 v2, v0
	s_add_i32 s0, 0, 0x25804
	v_mov_b32_e32 v0, s0
	ds_read_b32 v0, v0
	s_waitcnt lgkmcnt(1)
	v_cmp_ne_u32_e32 vcc, 0, v2
	s_cbranch_vccnz .LBB0_1697
	s_add_u32 s8, s26, 0xc0200
	s_addc_u32 s9, s27, 0
	s_add_u32 s4, s26, 0xc0400
	s_addc_u32 s5, s27, 0
	s_add_u32 s10, s26, 0xc0500
	s_addc_u32 s11, s27, 0
	s_add_u32 s12, s26, 0xc0600
	s_addc_u32 s13, s27, 0
	s_add_u32 s14, s26, 0xc0700
	s_addc_u32 s15, s27, 0
	s_add_u32 s16, s26, 0xc0800
	s_addc_u32 s17, s27, 0
	s_add_u32 s18, s26, 0xc0900
	s_addc_u32 s19, s27, 0
	s_add_u32 s20, s26, 0xc0a00
	s_addc_u32 s21, s27, 0
	s_add_u32 s36, s26, 0xc0b00
	s_addc_u32 s37, s27, 0
	s_add_u32 s38, s26, 0xc0c00
	s_addc_u32 s39, s27, 0
	s_add_u32 s42, s26, 0xc0d00
	s_addc_u32 s43, s27, 0
	s_add_u32 s44, s26, 0xc0e00
	s_addc_u32 s45, s27, 0
	s_add_u32 s46, s26, 0xc0f00
	s_addc_u32 s47, s27, 0
	s_add_u32 s50, s26, 0xc1000
	s_addc_u32 s51, s27, 0
	s_add_u32 s52, s26, 0xc1100
	s_addc_u32 s53, s27, 0
	s_add_u32 s54, s26, 0xc1200
	v_readlane_b32 s0, v255, 0
	s_addc_u32 s55, s27, 0
	s_mul_i32 s23, s31, s0
	s_add_u32 s56, s26, 0xc1300
	s_mul_i32 s23, s23, s30
	s_addc_u32 s57, s27, 0
	s_mov_b32 s24, 1
	v_mov_b32_e32 v16, 0
	s_branch .LBB0_1685

.LBB0_1712:
	s_or_b64 exec, exec, s[0:1]
	s_waitcnt vmcnt(0)
.LBB0_1713:
	s_andn2_saveexec_b64 s[10:11], s[4:5]
	s_cbranch_execz .LBB0_1733
	s_mov_b64 s[0:1], exec
	buffer_wbl2 sc1
	s_waitcnt lgkmcnt(0)
	s_waitcnt vmcnt(0)
	v_mbcnt_lo_u32_b32 v1, s0, 0
	v_mbcnt_hi_u32_b32 v1, s1, v1
	v_cmp_eq_u32_e32 vcc, 0, v1
	s_and_saveexec_b64 s[4:5], vcc
	s_cbranch_execz .LBB0_1716
	s_bcnt1_i32_b64 s0, s[0:1]
	v_mov_b32_e32 v2, 0xc3000
	v_mov_b32_e32 v3, s0
	global_atomic_add v2, v2, v3, s[26:27] offset:1024 sc0

.LBB0_1754:
	s_waitcnt vmcnt(0)
	v_readlane_b32 s2, v255, 4
	v_readlane_b32 s3, v255, 5
	s_waitcnt lgkmcnt(0)
	s_setprio 0
	s_barrier
	s_and_saveexec_b64 s[0:1], s[2:3]
	s_xor_b64 s[2:3], exec, s[0:1]
	s_cbranch_execz .LBB0_1807
	s_add_i32 s0, 0, 0x25800
	v_mov_b32_e32 v0, s0
	s_waitcnt vmcnt(0) expcnt(0) lgkmcnt(0)
	buffer_inv sc1
	ds_read_b32 v2, v0
	s_add_i32 s0, 0, 0x25804
	v_mov_b32_e32 v0, s0
	ds_read_b32 v0, v0
	s_waitcnt lgkmcnt(1)
	v_cmp_ne_u32_e32 vcc, 0, v2
	s_cbranch_vccnz .LBB0_1770
	s_add_u32 s4, s26, 0xc0200
	v_readlane_b32 s0, v255, 0
	s_addc_u32 s5, s27, 0
	s_mul_i32 s23, s31, s0
	s_add_u32 s0, s26, 0xc0400
	s_addc_u32 s1, s27, 0
	s_add_u32 s6, s26, 0xc0500
	s_addc_u32 s7, s27, 0
	s_add_u32 s8, s26, 0xc0600
	s_addc_u32 s9, s27, 0
	s_add_u32 s10, s26, 0xc0700
	s_addc_u32 s11, s27, 0
	s_add_u32 s12, s26, 0xc0800
	s_addc_u32 s13, s27, 0
	s_add_u32 s14, s26, 0xc0900
	s_addc_u32 s15, s27, 0
	s_add_u32 s16, s26, 0xc0a00
	s_addc_u32 s17, s27, 0
	s_add_u32 s18, s26, 0xc0b00
	s_addc_u32 s19, s27, 0
	s_add_u32 s20, s26, 0xc0c00
	s_addc_u32 s21, s27, 0
	s_mul_i32 s23, s23, s30
	s_add_u32 s30, s26, 0xc0d00
	s_addc_u32 s31, s27, 0
	s_add_u32 s34, s26, 0xc0e00
	s_addc_u32 s35, s27, 0
	s_add_u32 s36, s26, 0xc0f00
	s_addc_u32 s37, s27, 0
	s_add_u32 s38, s26, 0xc1000
	s_addc_u32 s39, s27, 0
	s_add_u32 s40, s26, 0xc1100
	s_addc_u32 s41, s27, 0
	s_add_u32 s42, s26, 0xc1200
	s_addc_u32 s43, s27, 0
	s_add_u32 s44, s26, 0xc1300
	s_addc_u32 s45, s27, 0
	s_mov_b32 s24, 1
	v_mov_b32_e32 v16, 0
	s_branch .LBB0_1758

.LBB0_1785:
	s_or_b64 exec, exec, s[6:7]
	s_waitcnt vmcnt(0)
.LBB0_1786:
	s_andn2_saveexec_b64 s[6:7], s[0:1]
	s_cbranch_execz .LBB0_1806
	s_mov_b64 s[0:1], exec
	buffer_wbl2 sc1
	s_waitcnt lgkmcnt(0)
	s_waitcnt vmcnt(0)
	v_mbcnt_lo_u32_b32 v1, s0, 0
	v_mbcnt_hi_u32_b32 v1, s1, v1
	v_cmp_eq_u32_e32 vcc, 0, v1
	s_and_saveexec_b64 s[8:9], vcc
	s_cbranch_execz .LBB0_1789
	s_bcnt1_i32_b64 s0, s[0:1]
	v_mov_b32_e32 v2, 0xc3000
	v_mov_b32_e32 v3, s0
	global_atomic_add v2, v2, v3, s[26:27] offset:1024 sc0
